# t15 with the 4 K tile DMAs issued before the K fragment ds_reads (first thing after the step barrier)
# speedup vs baseline: 1.0146x; 1.0146x over previous
; __device__ __forceinline__ void partialSM(f32x16& p0, f32x16& p1, float& m_reg, float& mn, float& alpha) {
;   constexpr float C = SCALE * L2E;
;   float pmax = p0[0];
; #pragma unroll
;   for (int r = 1; r < 16; ++r) pmax = fmaxf(pmax, p0[r]);
; #pragma unroll
;   for (int r = 0; r < 16; ++r) pmax = fmaxf(pmax, p1[r]);
;   { auto rr = __builtin_amdgcn_permlane32_swap(__float_as_uint(pmax), __float_as_uint(pmax), false, false);
;     pmax = fmaxf(__uint_as_float(rr[0]), __uint_as_float(rr[1])); }
;   if (__builtin_expect(__all(pmax - m_reg <= THR / SCALE), 1)) { mn = m_reg; alpha = 1.f; }
;   else { mn = fmaxf(m_reg, pmax); alpha = __builtin_amdgcn_exp2f((m_reg - mn) * C); m_reg = mn; }
;   float mnC = -mn * C;
; #pragma unroll
;   for (int r = 0; r < 16; ++r) p0[r] = fmaf(p0[r], C, mnC);
; #pragma unroll
;   for (int r = 0; r < 16; ++r) p1[r] = fmaf(p1[r], C, mnC);
; #pragma unroll
;   for (int r = 0; r < 16; ++r) p0[r] = __builtin_amdgcn_exp2f(p0[r]);
; }
; __device__ __forceinline__ void finishSM(f32x16& p0, f32x16& p1, float alpha, float& l_reg, bf16x8& pa0, bf16x8& pa1, bf16x8& pa2, bf16x8& pa3) {
; #pragma unroll
;   for (int r = 0; r < 16; ++r) p1[r] = __builtin_amdgcn_exp2f(p1[r]);
;   float ps = 0;
; #pragma unroll
;   for (int r = 0; r < 16; ++r) ps += p0[r];
; #pragma unroll
;   for (int r = 0; r < 16; ++r) ps += p1[r];
;   { auto rr = __builtin_amdgcn_permlane32_swap(__float_as_uint(ps), __float_as_uint(ps), false, false);
;     ps = __uint_as_float(rr[0]) + __uint_as_float(rr[1]); }
;   l_reg = l_reg * alpha + ps;
.LBB0_508:
	s_cmpk_gt_u32 s71, 0x7d
	s_cselect_b64 s[48:49], -1, 0
	s_add_i32 s8, s72, 0xffffe000
	s_cmpk_lt_u32 s71, 0x7e
	s_cselect_b32 s8, s8, 0xfe000
	s_lshl_b64 s[84:85], s[8:9], 1
	s_add_u32 s84, s46, s84
	s_addc_u32 s85, s47, s85
	s_mov_b32 m0, s64
	s_nop 0
	global_load_lds_dwordx4 v0, s[84:85]
	s_mov_b32 m0, s2
	s_nop 0
	global_load_lds_dwordx4 v236, s[84:85]
	s_mov_b32 m0, s3
	s_nop 0
	global_load_lds_dwordx4 v237, s[84:85]
	s_mov_b32 m0, s66
	s_nop 0
	global_load_lds_dwordx4 v238, s[84:85]
	ds_read_b128 v[200:203], v108
	ds_read_b128 v[204:207], v108 offset:8192
	ds_read_b128 v[208:211], v109
	ds_read_b128 v[212:215], v109 offset:8192
	ds_read_b128 v[216:219], v110
	ds_read_b128 v[220:223], v110 offset:8192
	ds_read_b128 v[224:227], v111
	ds_read_b128 v[228:231], v111 offset:8192
	v_max_f32_e32 v99, v19, v19
	v_max_f32_e32 v118, v18, v18
	v_max_f32_e32 v99, v118, v99
	v_max3_f32 v99, v99, v20, v21
	v_max3_f32 v99, v99, v22, v23
	v_max3_f32 v99, v99, v24, v25
	v_max3_f32 v99, v99, v26, v27
	v_max3_f32 v99, v99, v28, v29
	v_max3_f32 v99, v99, v30, v31
	v_max3_f32 v99, v99, v32, v33
	s_waitcnt lgkmcnt(6)
	v_mfma_f32_32x32x16_bf16 v[50:65], v[200:203], v[66:69], 0
	v_max3_f32 v99, v99, v2, v3
	v_max3_f32 v99, v99, v4, v5
	v_max3_f32 v99, v99, v6, v7
	v_max3_f32 v99, v99, v8, v9
	v_max3_f32 v99, v99, v10, v11
	v_max3_f32 v99, v99, v12, v13
	v_max3_f32 v99, v99, v14, v15
	v_max3_f32 v99, v99, v16, v17
	v_mov_b32_e32 v118, v99
	v_mfma_f32_32x32x16_bf16 v[34:49], v[204:207], v[66:69], 0
	ds_read_b128 v[200:203], v113
	ds_read_b128 v[204:207], v113 offset:8192
	s_nop 1
	v_permlane32_swap_b32_e32 v99, v118
	v_max_f32_e32 v118, v118, v118
	v_max_f32_e32 v99, v99, v99
	v_max_f32_e32 v99, v99, v118
	v_sub_f32_e32 v118, v99, v121
	v_cmp_ge_f32_e32 vcc, s61, v118
	v_max_f32_e32 v119, v121, v121
	s_cmp_eq_u64 vcc, exec
	v_max_f32_e32 v99, v119, v99
	s_cselect_b64 vcc, -1, 0
	s_waitcnt lgkmcnt(6)
	v_mfma_f32_32x32x16_bf16 v[50:65], v[208:211], v[70:73], v[50:65]
	v_sub_f32_e32 v119, v121, v99
	v_cndmask_b32_e32 v121, v99, v121, vcc
	v_mul_f32_e32 v99, 0xbe0293ee, v121
	v_fmamk_f32 v18, v18, 0x3e0293ee, v99
	v_fmamk_f32 v19, v19, 0x3e0293ee, v99
	v_fmamk_f32 v20, v20, 0x3e0293ee, v99
	v_fmamk_f32 v21, v21, 0x3e0293ee, v99
	v_fmamk_f32 v22, v22, 0x3e0293ee, v99
	v_mfma_f32_32x32x16_bf16 v[34:49], v[212:215], v[70:73], v[34:49]
	ds_read_b128 v[208:211], v114
	ds_read_b128 v[212:215], v114 offset:8192
	v_fmamk_f32 v23, v23, 0x3e0293ee, v99
	v_fmamk_f32 v24, v24, 0x3e0293ee, v99
	v_fmamk_f32 v25, v25, 0x3e0293ee, v99
	v_fmamk_f32 v26, v26, 0x3e0293ee, v99
	v_fmamk_f32 v27, v27, 0x3e0293ee, v99
	v_fmamk_f32 v28, v28, 0x3e0293ee, v99
	v_fmamk_f32 v29, v29, 0x3e0293ee, v99
	v_fmamk_f32 v30, v30, 0x3e0293ee, v99
	v_fmamk_f32 v31, v31, 0x3e0293ee, v99
	s_waitcnt lgkmcnt(6)
	v_mfma_f32_32x32x16_bf16 v[50:65], v[216:219], v[74:77], v[50:65]
	v_fmamk_f32 v32, v32, 0x3e0293ee, v99
	v_fmamk_f32 v33, v33, 0x3e0293ee, v99
	v_fmamk_f32 v2, v2, 0x3e0293ee, v99
	v_fmamk_f32 v3, v3, 0x3e0293ee, v99
	v_fmamk_f32 v4, v4, 0x3e0293ee, v99
	v_fmamk_f32 v5, v5, 0x3e0293ee, v99
	v_fmamk_f32 v6, v6, 0x3e0293ee, v99
	v_fmamk_f32 v7, v7, 0x3e0293ee, v99
	v_fmamk_f32 v8, v8, 0x3e0293ee, v99
	v_mfma_f32_32x32x16_bf16 v[34:49], v[220:223], v[74:77], v[34:49]
	ds_read_b128 v[216:219], v115
	ds_read_b128 v[220:223], v115 offset:8192
	v_fmamk_f32 v9, v9, 0x3e0293ee, v99
	v_fmamk_f32 v10, v10, 0x3e0293ee, v99
	v_fmamk_f32 v11, v11, 0x3e0293ee, v99
	v_fmamk_f32 v12, v12, 0x3e0293ee, v99
	v_fmamk_f32 v13, v13, 0x3e0293ee, v99
	v_fmamk_f32 v14, v14, 0x3e0293ee, v99
	v_fmamk_f32 v15, v15, 0x3e0293ee, v99
	v_fmamk_f32 v16, v16, 0x3e0293ee, v99
	v_fmac_f32_e32 v99, 0x3e0293ee, v17
	v_exp_f32_e32 v17, v18
	s_waitcnt lgkmcnt(6)
	v_mfma_f32_32x32x16_bf16 v[50:65], v[224:227], v[78:81], v[50:65]
	v_exp_f32_e32 v18, v19
	v_exp_f32_e32 v19, v20
	v_exp_f32_e32 v20, v21
	v_exp_f32_e32 v21, v22
	v_exp_f32_e32 v22, v23
	v_exp_f32_e32 v23, v24
	v_exp_f32_e32 v24, v25
	v_exp_f32_e32 v25, v26
	v_exp_f32_e32 v26, v27
	v_mfma_f32_32x32x16_bf16 v[34:49], v[228:231], v[78:81], v[34:49]
	ds_read_b128 v[224:227], v116
	ds_read_b128 v[228:231], v116 offset:8192
	v_exp_f32_e32 v27, v28
	v_exp_f32_e32 v28, v29
	v_exp_f32_e32 v29, v30
	v_exp_f32_e32 v30, v31
	v_exp_f32_e32 v31, v32
	v_exp_f32_e32 v32, v33
	v_exp_f32_e32 v33, v2
	v_add_f32_e32 v2, 0, v17
	v_add_f32_e32 v2, v18, v2
	s_waitcnt lgkmcnt(6)
	v_mfma_f32_32x32x16_bf16 v[50:65], v[200:203], v[82:85], v[50:65]
	v_add_f32_e32 v2, v19, v2
	v_add_f32_e32 v2, v20, v2
	v_add_f32_e32 v2, v21, v2
	v_add_f32_e32 v2, v22, v2
	v_add_f32_e32 v2, v23, v2
	v_add_f32_e32 v2, v24, v2
	v_add_f32_e32 v2, v25, v2
	v_add_f32_e32 v2, v26, v2
	v_add_f32_e32 v2, v27, v2
	v_add_f32_e32 v2, v28, v2
	v_mfma_f32_32x32x16_bf16 v[34:49], v[204:207], v[82:85], v[34:49]
	v_add_f32_e32 v2, v29, v2
	v_exp_f32_e32 v122, v3
	v_add_f32_e32 v2, v30, v2
	v_exp_f32_e32 v123, v4
	v_add_f32_e32 v2, v31, v2
	v_exp_f32_e32 v124, v5
	v_add_f32_e32 v2, v32, v2
	v_exp_f32_e32 v125, v6
	v_add_f32_e32 v2, v33, v2
	s_waitcnt lgkmcnt(4)
	v_mfma_f32_32x32x16_bf16 v[50:65], v[208:211], v[86:89], v[50:65]
	v_exp_f32_e32 v126, v7
	v_add_f32_e32 v2, v122, v2
	v_exp_f32_e32 v127, v8
	v_add_f32_e32 v2, v123, v2
	v_exp_f32_e32 v128, v9
	v_add_f32_e32 v2, v124, v2
	v_exp_f32_e32 v129, v10
	v_add_f32_e32 v2, v125, v2
	v_exp_f32_e32 v130, v11
	v_mfma_f32_32x32x16_bf16 v[34:49], v[212:215], v[86:89], v[34:49]
	v_add_f32_e32 v2, v126, v2
	v_exp_f32_e32 v131, v12
	v_add_f32_e32 v2, v127, v2
	v_exp_f32_e32 v132, v13
	v_add_f32_e32 v2, v128, v2
	v_mul_f32_e32 v119, 0x3e0293ee, v119
	v_exp_f32_e32 v133, v14
	v_add_f32_e32 v2, v129, v2
	v_exp_f32_e32 v119, v119
	v_exp_f32_e32 v134, v15
	s_waitcnt lgkmcnt(2)
; __device__ __forceinline__ void finishSM(f32x16& p0, f32x16& p1, float alpha, float& l_reg, bf16x8& pa0, bf16x8& pa1, bf16x8& pa2, bf16x8& pa3) {
; #pragma unroll
;   for (int r = 0; r < 16; ++r) p1[r] = __builtin_amdgcn_exp2f(p1[r]);
;   float ps = 0;
; #pragma unroll
;   for (int r = 0; r < 16; ++r) ps += p0[r];
; #pragma unroll
;   for (int r = 0; r < 16; ++r) ps += p1[r];
;   { auto rr = __builtin_amdgcn_permlane32_swap(__float_as_uint(ps), __float_as_uint(ps), false, false);
;     ps = __uint_as_float(rr[0]) + __uint_as_float(rr[1]); }
;   l_reg = l_reg * alpha + ps;
;     ...
;   PK4(p0, 0, pa0); PK4(p0, 8, pa1); PK4(p1, 0, pa2); PK4(p1, 8, pa3);
;     ...
; }
	v_mfma_f32_32x32x16_bf16 v[50:65], v[216:219], v[90:93], v[50:65]
	v_add_f32_e32 v2, v130, v2
	v_exp_f32_e32 v135, v16
	v_add_f32_e32 v2, v131, v2
	v_exp_f32_e32 v99, v99
	v_add_f32_e32 v2, v132, v2
	v_add_f32_e32 v2, v133, v2
	v_cndmask_b32_e64 v118, v119, 1.0, vcc
	v_add_f32_e32 v2, v134, v2
	v_add_f32_e32 v2, v135, v2
	v_mfma_f32_32x32x16_bf16 v[34:49], v[220:223], v[90:93], v[34:49]
	v_cmp_gt_f32_e32 vcc, 1.0, v118
	v_add_f32_e32 v119, v99, v2
	s_cmp_lg_u64 vcc, 0
	v_mov_b32_e32 v120, v119
	v_cvt_pk_bf16_f32 v2, v17, v18
	v_cvt_pk_bf16_f32 v3, v19, v20
	v_cvt_pk_bf16_f32 v4, v21, v22
	v_cvt_pk_bf16_f32 v5, v23, v24
	s_cselect_b64 s[50:51], -1, 0
	s_waitcnt lgkmcnt(0)
	v_mfma_f32_32x32x16_bf16 v[50:65], v[224:227], v[94:97], v[50:65]
	s_nop 0
	v_permlane32_swap_b32_e32 v119, v120
	v_permlane32_swap_b32_e32 v2, v4
	v_permlane32_swap_b32_e32 v3, v5
	v_cvt_pk_bf16_f32 v6, v25, v26
	v_cvt_pk_bf16_f32 v7, v27, v28
	v_cvt_pk_bf16_f32 v8, v29, v30
	v_cvt_pk_bf16_f32 v9, v31, v32
	v_cvt_pk_bf16_f32 v10, v33, v122
	v_cvt_pk_bf16_f32 v11, v123, v124
	v_mfma_f32_32x32x16_bf16 v[34:49], v[228:231], v[94:97], v[34:49]
	v_cvt_pk_bf16_f32 v12, v125, v126
	v_cvt_pk_bf16_f32 v13, v127, v128
	v_cvt_pk_bf16_f32 v14, v129, v130
	v_cvt_pk_bf16_f32 v15, v131, v132
	v_cvt_pk_bf16_f32 v16, v133, v134
	v_cvt_pk_bf16_f32 v17, v135, v99
	s_and_b64 s[74:75], s[50:51], s[0:1]
	v_permlane32_swap_b32_e32 v6, v8
	v_permlane32_swap_b32_e32 v7, v9
	v_permlane32_swap_b32_e32 v10, v12
	v_permlane32_swap_b32_e32 v11, v13
	v_permlane32_swap_b32_e32 v14, v16
	v_permlane32_swap_b32_e32 v15, v17
	ds_write_b128 v179, v[2:5]
	ds_write_b128 v179, v[6:9] offset:1024
	ds_write_b128 v179, v[10:13] offset:2048
	ds_write_b128 v179, v[14:17] offset:3072
	s_and_saveexec_b64 s[52:53], s[74:75]
	ds_write_b32 v117, v118
	s_or_b64 exec, exec, s[52:53]
	s_and_saveexec_b64 s[52:53], s[4:5]
	v_cndmask_b32_e64 v2, 0, 1.0, s[50:51]
	v_mov_b32_e32 v3, s65
	ds_write_b32 v3, v2 offset:128
	s_or_b64 exec, exec, s[52:53]
	s_waitcnt vmcnt(0)
	s_waitcnt lgkmcnt(0)
	s_barrier
	s_cmpk_lt_u32 s71, 0x7d
	s_cselect_b32 s8, s72, 0xfe000
	s_lshl_b64 s[84:85], s[8:9], 1
	s_add_u32 s84, s46, s84
	s_addc_u32 s85, s47, s85
	s_mov_b32 m0, s67
	s_nop 0
	global_load_lds_dwordx4 v0, s[84:85]
	s_mov_b32 m0, s68
	s_nop 0
	global_load_lds_dwordx4 v236, s[84:85]
	s_mov_b32 m0, s69
	s_nop 0
	global_load_lds_dwordx4 v237, s[84:85]
	s_mov_b32 m0, s70
	s_nop 0
	global_load_lds_dwordx4 v238, s[84:85]
	ds_read_b128 v[200:203], v100
	ds_read_b128 v[204:207], v100 offset:8192
	ds_read_b128 v[208:211], v101
	ds_read_b128 v[212:215], v101 offset:8192
	ds_read_b128 v[216:219], v102
	ds_read_b128 v[220:223], v102 offset:8192
	ds_read_b128 v[224:227], v103
	ds_read_b128 v[228:231], v103 offset:8192
	v_max_f32_e32 v99, v51, v51
	v_max_f32_e32 v122, v50, v50
	v_max_f32_e32 v99, v122, v99
	v_max3_f32 v99, v99, v52, v53
	v_max3_f32 v99, v99, v54, v55
	v_max3_f32 v99, v99, v56, v57
	v_max3_f32 v99, v99, v58, v59
	v_max3_f32 v99, v99, v60, v61
	v_max3_f32 v99, v99, v62, v63
	v_max3_f32 v99, v99, v64, v65
	s_waitcnt lgkmcnt(6)
	v_mfma_f32_32x32x16_bf16 v[18:33], v[200:203], v[66:69], 0
	v_max3_f32 v99, v99, v34, v35
	v_max3_f32 v99, v99, v36, v37
	v_max3_f32 v99, v99, v38, v39
	v_max3_f32 v99, v99, v40, v41
	v_max3_f32 v99, v99, v42, v43
	v_max3_f32 v99, v99, v44, v45
	v_max3_f32 v99, v99, v46, v47
	v_max3_f32 v99, v99, v48, v49
	v_mov_b32_e32 v122, v99
	v_mfma_f32_32x32x16_bf16 v[2:17], v[204:207], v[66:69], 0
	ds_read_b128 v[200:203], v104
	ds_read_b128 v[204:207], v104 offset:8192
	s_nop 1
	v_permlane32_swap_b32_e32 v99, v122
	v_max_f32_e32 v122, v122, v122
	v_max_f32_e32 v99, v99, v99
	v_max_f32_e32 v99, v99, v122
	v_sub_f32_e32 v122, v99, v121
	v_cmp_ge_f32_e32 vcc, s61, v122
	v_max_f32_e32 v123, v121, v121
	s_cmp_eq_u64 vcc, exec
	v_max_f32_e32 v123, v123, v99
	s_cselect_b64 vcc, -1, 0
	s_waitcnt lgkmcnt(6)
	v_mfma_f32_32x32x16_bf16 v[18:33], v[208:211], v[70:73], v[18:33]
	v_sub_f32_e32 v99, v121, v123
	v_cndmask_b32_e32 v121, v123, v121, vcc
	v_mul_f32_e32 v122, 0xbe0293ee, v121
	v_fmamk_f32 v50, v50, 0x3e0293ee, v122
	v_fmamk_f32 v51, v51, 0x3e0293ee, v122
	v_fmamk_f32 v52, v52, 0x3e0293ee, v122
	v_fmamk_f32 v53, v53, 0x3e0293ee, v122
	v_fmamk_f32 v54, v54, 0x3e0293ee, v122
	v_mfma_f32_32x32x16_bf16 v[2:17], v[212:215], v[70:73], v[2:17]
	ds_read_b128 v[208:211], v105
	ds_read_b128 v[212:215], v105 offset:8192
	v_fmamk_f32 v55, v55, 0x3e0293ee, v122
	v_fmamk_f32 v56, v56, 0x3e0293ee, v122
	v_fmamk_f32 v57, v57, 0x3e0293ee, v122
	v_fmamk_f32 v58, v58, 0x3e0293ee, v122
	v_fmamk_f32 v59, v59, 0x3e0293ee, v122
	v_fmamk_f32 v60, v60, 0x3e0293ee, v122
	v_fmamk_f32 v61, v61, 0x3e0293ee, v122
	v_fmamk_f32 v62, v62, 0x3e0293ee, v122
	v_fmamk_f32 v63, v63, 0x3e0293ee, v122
	s_waitcnt lgkmcnt(6)
; __device__ __forceinline__ void partialSM(f32x16& p0, f32x16& p1, float& m_reg, float& mn, float& alpha) {
;     ...
;   for (int r = 0; r < 16; ++r) p0[r] = fmaf(p0[r], C, mnC);
; #pragma unroll
;   for (int r = 0; r < 16; ++r) p1[r] = fmaf(p1[r], C, mnC);
; #pragma unroll
;   for (int r = 0; r < 16; ++r) p0[r] = __builtin_amdgcn_exp2f(p0[r]);
; }
; __device__ __forceinline__ void finishSM(f32x16& p0, f32x16& p1, float alpha, float& l_reg, bf16x8& pa0, bf16x8& pa1, bf16x8& pa2, bf16x8& pa3) {
; #pragma unroll
;   for (int r = 0; r < 16; ++r) p1[r] = __builtin_amdgcn_exp2f(p1[r]);
;   float ps = 0;
; #pragma unroll
;   for (int r = 0; r < 16; ++r) ps += p0[r];
; #pragma unroll
;   for (int r = 0; r < 16; ++r) ps += p1[r];
;   { auto rr = __builtin_amdgcn_permlane32_swap(__float_as_uint(ps), __float_as_uint(ps), false, false);
;     ps = __uint_as_float(rr[0]) + __uint_as_float(rr[1]); }
;   l_reg = l_reg * alpha + ps;
;     ...
;   PK4(p0, 0, pa0); PK4(p0, 8, pa1); PK4(p1, 0, pa2); PK4(p1, 8, pa3);
	v_mfma_f32_32x32x16_bf16 v[18:33], v[216:219], v[74:77], v[18:33]
	v_fmamk_f32 v64, v64, 0x3e0293ee, v122
	v_fmamk_f32 v65, v65, 0x3e0293ee, v122
	v_fmamk_f32 v34, v34, 0x3e0293ee, v122
	v_fmamk_f32 v35, v35, 0x3e0293ee, v122
	v_fmamk_f32 v36, v36, 0x3e0293ee, v122
	v_fmamk_f32 v37, v37, 0x3e0293ee, v122
	v_fmamk_f32 v38, v38, 0x3e0293ee, v122
	v_fmamk_f32 v39, v39, 0x3e0293ee, v122
	v_fmamk_f32 v40, v40, 0x3e0293ee, v122
	v_mfma_f32_32x32x16_bf16 v[2:17], v[220:223], v[74:77], v[2:17]
	ds_read_b128 v[216:219], v106
	ds_read_b128 v[220:223], v106 offset:8192
	v_fmamk_f32 v41, v41, 0x3e0293ee, v122
	v_fmamk_f32 v42, v42, 0x3e0293ee, v122
	v_fmamk_f32 v43, v43, 0x3e0293ee, v122
	v_fmamk_f32 v44, v44, 0x3e0293ee, v122
	v_fmamk_f32 v45, v45, 0x3e0293ee, v122
	v_fmamk_f32 v46, v46, 0x3e0293ee, v122
	v_fmamk_f32 v47, v47, 0x3e0293ee, v122
	v_fmamk_f32 v48, v48, 0x3e0293ee, v122
	v_fmac_f32_e32 v122, 0x3e0293ee, v49
	v_exp_f32_e32 v49, v50
	s_waitcnt lgkmcnt(6)
	v_mfma_f32_32x32x16_bf16 v[18:33], v[224:227], v[78:81], v[18:33]
	v_exp_f32_e32 v50, v51
	v_exp_f32_e32 v51, v52
	v_exp_f32_e32 v52, v53
	v_exp_f32_e32 v53, v54
	v_exp_f32_e32 v54, v55
	v_exp_f32_e32 v55, v56
	v_exp_f32_e32 v56, v57
	v_exp_f32_e32 v57, v58
	v_exp_f32_e32 v58, v59
	v_mfma_f32_32x32x16_bf16 v[2:17], v[228:231], v[78:81], v[2:17]
	ds_read_b128 v[224:227], v107
	ds_read_b128 v[228:231], v107 offset:8192
	v_exp_f32_e32 v59, v60
	v_exp_f32_e32 v60, v61
	v_exp_f32_e32 v61, v62
	v_exp_f32_e32 v62, v63
	v_exp_f32_e32 v63, v64
	v_exp_f32_e32 v64, v65
	v_exp_f32_e32 v65, v34
	v_add_f32_e32 v34, 0, v49
	v_add_f32_e32 v34, v50, v34
	s_waitcnt lgkmcnt(6)
	v_mfma_f32_32x32x16_bf16 v[18:33], v[200:203], v[82:85], v[18:33]
	v_add_f32_e32 v34, v51, v34
	v_add_f32_e32 v34, v52, v34
	v_add_f32_e32 v34, v53, v34
	v_add_f32_e32 v34, v54, v34
	v_add_f32_e32 v34, v55, v34
	v_add_f32_e32 v34, v56, v34
	v_add_f32_e32 v34, v57, v34
	v_add_f32_e32 v34, v58, v34
	v_add_f32_e32 v34, v59, v34
	v_add_f32_e32 v34, v60, v34
	v_mfma_f32_32x32x16_bf16 v[2:17], v[204:207], v[82:85], v[2:17]
	v_add_f32_e32 v34, v61, v34
	v_exp_f32_e32 v123, v35
	v_add_f32_e32 v34, v62, v34
	v_exp_f32_e32 v124, v36
	v_add_f32_e32 v34, v63, v34
	v_exp_f32_e32 v125, v37
	v_add_f32_e32 v34, v64, v34
	v_exp_f32_e32 v126, v38
	v_add_f32_e32 v34, v65, v34
	s_waitcnt lgkmcnt(4)
	v_mfma_f32_32x32x16_bf16 v[18:33], v[208:211], v[86:89], v[18:33]
	v_exp_f32_e32 v127, v39
	v_add_f32_e32 v34, v123, v34
	v_exp_f32_e32 v128, v40
	v_add_f32_e32 v34, v124, v34
	v_exp_f32_e32 v129, v41
	v_add_f32_e32 v34, v125, v34
	v_exp_f32_e32 v130, v42
	v_add_f32_e32 v34, v126, v34
	v_exp_f32_e32 v131, v43
	v_mfma_f32_32x32x16_bf16 v[2:17], v[212:215], v[86:89], v[2:17]
	v_add_f32_e32 v34, v127, v34
	v_exp_f32_e32 v132, v44
	v_add_f32_e32 v34, v128, v34
	v_exp_f32_e32 v133, v45
	v_add_f32_e32 v34, v129, v34
	v_mul_f32_e32 v99, 0x3e0293ee, v99
	v_exp_f32_e32 v134, v46
	v_add_f32_e32 v34, v130, v34
	v_exp_f32_e32 v99, v99
	v_exp_f32_e32 v135, v47
	s_waitcnt lgkmcnt(2)
	v_mfma_f32_32x32x16_bf16 v[18:33], v[216:219], v[90:93], v[18:33]
	v_add_f32_e32 v34, v131, v34
	v_exp_f32_e32 v136, v48
	v_add_f32_e32 v34, v132, v34
	v_exp_f32_e32 v122, v122
	v_add_f32_e32 v34, v133, v34
	v_add_f32_e32 v34, v134, v34
	v_cndmask_b32_e64 v99, v99, 1.0, vcc
	v_add_f32_e32 v34, v135, v34
	v_add_f32_e32 v34, v136, v34
	v_mfma_f32_32x32x16_bf16 v[2:17], v[220:223], v[90:93], v[2:17]
	v_cmp_gt_f32_e32 vcc, 1.0, v99
	v_add_f32_e32 v34, v122, v34
	s_cmp_lg_u64 vcc, 0
	v_mov_b32_e32 v35, v34
	v_cvt_pk_bf16_f32 v36, v49, v50
	v_cvt_pk_bf16_f32 v37, v51, v52
	v_cvt_pk_bf16_f32 v38, v53, v54
	v_cvt_pk_bf16_f32 v39, v55, v56
	s_cselect_b64 s[50:51], -1, 0
	s_waitcnt lgkmcnt(0)
	v_mfma_f32_32x32x16_bf16 v[18:33], v[224:227], v[94:97], v[18:33]
	s_nop 0
	v_permlane32_swap_b32_e32 v34, v35
	v_permlane32_swap_b32_e32 v36, v38
	v_permlane32_swap_b32_e32 v37, v39
	v_cvt_pk_bf16_f32 v40, v57, v58
	v_cvt_pk_bf16_f32 v41, v59, v60
	v_cvt_pk_bf16_f32 v42, v61, v62
	v_cvt_pk_bf16_f32 v43, v63, v64
	v_cvt_pk_bf16_f32 v44, v65, v123
	v_cvt_pk_bf16_f32 v45, v124, v125
	v_mfma_f32_32x32x16_bf16 v[2:17], v[228:231], v[94:97], v[2:17]
	v_cvt_pk_bf16_f32 v46, v126, v127
	v_cvt_pk_bf16_f32 v47, v128, v129
	v_cvt_pk_bf16_f32 v48, v130, v131
	v_cvt_pk_bf16_f32 v49, v132, v133
	v_cvt_pk_bf16_f32 v50, v134, v135
	v_cvt_pk_bf16_f32 v51, v136, v122
	s_and_b64 s[74:75], s[50:51], s[0:1]
	v_permlane32_swap_b32_e32 v40, v42
	v_permlane32_swap_b32_e32 v41, v43
	v_permlane32_swap_b32_e32 v44, v46
	v_permlane32_swap_b32_e32 v45, v47
	v_permlane32_swap_b32_e32 v48, v50
	v_permlane32_swap_b32_e32 v49, v51
	ds_write_b128 v179, v[36:39] offset:16384
	ds_write_b128 v179, v[40:43] offset:17408
	ds_write_b128 v179, v[44:47] offset:18432
	ds_write_b128 v179, v[48:51] offset:19456
	s_and_saveexec_b64 s[52:53], s[74:75]
	ds_write_b32 v117, v99 offset:1024
	s_or_b64 exec, exec, s[52:53]
	s_and_saveexec_b64 s[52:53], s[4:5]
	s_cbranch_execz .LBB0_507
	v_cndmask_b32_e64 v36, 0, 1.0, s[50:51]
	v_mov_b32_e32 v37, s65
	ds_write_b32 v37, v36 offset:1152
	s_branch .LBB0_507
